# GLA decay lower-bound loads: 16 serial dword loads issued together, per-element LDS-write waits removed (pass1 and pass3)
# baseline (speedup 1.0000x reference)
.LBB0_595:
	s_mul_hi_i32 s0, s8, 0x3e0f83e1
	s_lshr_b32 s1, s0, 31
	s_ashr_i32 s0, s0, 5
	s_add_i32 s0, s0, s1
	s_mul_i32 s1, s0, 0x84
	s_sub_i32 s20, s8, s1
	s_and_b32 s19, s0, 1
	s_bfe_u32 s21, s0, 0x20001
	s_lshl_b32 s1, s20, 6
	s_cmp_lt_i32 s20, 4
	s_cselect_b32 s9, s7, s6
	v_mov_b32_e32 v16, v207
	s_add_i32 s9, s9, s1
	v_mov_b32_e32 v10, v207
	s_cmp_eq_u32 s19, 0
	s_barrier
	s_cselect_b64 s[42:43], -1, 0
	v_ashrrev_i32_e32 v4, 3, v10
	v_lshlrev_b32_e32 v0, 4, v10
	s_cmp_eq_u32 s19, 1
	v_and_b32_e32 v2, 0x70, v0
	v_add_u32_e32 v3, s9, v4
	v_mov_b64_e32 v[0:1], s[36:37]
	s_cselect_b64 s[2:3], -1, 0
	s_and_b32 s22, s0, -8
	v_mad_i64_i32 v[0:1], s[0:1], v3, s14, v[0:1]
	s_lshl_b32 s26, s21, 8
	s_lshl_b32 s18, s21, 7
	v_lshl_add_u64 v[0:1], v[0:1], 0, s[26:27]
	v_lshlrev_b32_e32 v128, 1, v2
	v_lshlrev_b32_e32 v3, 9, v4
	v_lshlrev_b32_e32 v5, 2, v2
	v_lshl_add_u64 v[0:1], v[0:1], 0, v[128:129]
	s_mov_b64 s[0:1], -1
	s_movk_i32 s100, 0xe00
	s_cmp_eq_u32 s22, 8
	s_cselect_b32 s100, 0x400, s100
	s_lshl_b32 s101, s21, 7
	s_add_i32 s100, s100, s101
	s_lshl_b32 s100, s100, 1
	s_mov_b32 s101, 0
	v_and_b32_e32 v162, 63, v207
	v_or_b32_e32 v162, s9, v162
	v_mul_u32_u24_e32 v162, 0x1200, v162
	v_mov_b32_e32 v163, 0
	v_lshl_add_u64 v[162:163], v[162:163], 1, s[36:37]
	v_lshl_add_u64 v[162:163], v[162:163], 0, s[100:101]
	v_ashrrev_i32_e32 v164, 2, v207
	v_and_b32_e32 v164, -16, v164
	v_mov_b32_e32 v165, 0
	v_lshl_add_u64 v[162:163], v[164:165], 1, v[162:163]
	global_load_dwordx4 v[154:157], v[162:163], off
	global_load_dwordx4 v[158:161], v[162:163], off offset:16
	s_cmp_lg_u32 s22, 8
	v_add3_u32 v5, 0, v3, v5
	s_cbranch_scc0 .LBB0_613
	s_and_b64 s[0:1], s[42:43], exec
	s_cselect_b32 s26, s15, 0x1800
	v_lshl_add_u64 v[12:13], v[0:1], 0, s[26:27]
	global_load_dwordx4 v[6:9], v[12:13], off
	global_load_dwordx4 v[26:29], v[12:13], off offset:16
	v_or_b32_e32 v2, s18, v2
	v_lshlrev_b32_e32 v128, 2, v2
	v_lshl_add_u64 v[2:3], s[78:79], 0, v[128:129]
	s_waitcnt vmcnt(0) lgkmcnt(0)
	v_lshlrev_b32_e32 v11, 16, v6
	v_and_b32_e32 v25, 0xffff0000, v6
	global_load_dword v6, v[2:3], off
	global_load_dword v182, v[2:3], off offset:4
	global_load_dword v183, v[2:3], off offset:8
	global_load_dword v184, v[2:3], off offset:12
	global_load_dword v185, v[2:3], off offset:16
	global_load_dword v186, v[2:3], off offset:20
	global_load_dword v187, v[2:3], off offset:24
	global_load_dword v188, v[2:3], off offset:28
	global_load_dword v189, v[2:3], off offset:32
	global_load_dword v190, v[2:3], off offset:36
	global_load_dword v191, v[2:3], off offset:40
	global_load_dword v238, v[2:3], off offset:44
	global_load_dword v239, v[2:3], off offset:48
	global_load_dword v240, v[2:3], off offset:52
	global_load_dword v241, v[2:3], off offset:56
	global_load_dword v242, v[2:3], off offset:60
	v_lshlrev_b32_e32 v15, 16, v8
	v_and_b32_e32 v12, 0xffff0000, v8
	v_mul_f32_e32 v8, 0xbfb8aa3b, v11
	v_exp_f32_e32 v8, v8
	v_lshlrev_b32_e32 v20, 16, v9
	v_and_b32_e32 v17, 0xffff0000, v9
	v_lshlrev_b32_e32 v24, 16, v26
	v_add_f32_e32 v8, 1.0, v8
	v_rcp_f32_e32 v11, v8
	v_and_b32_e32 v21, 0xffff0000, v26
	v_lshlrev_b32_e32 v23, 16, v27
	v_and_b32_e32 v22, 0xffff0000, v27
	v_lshlrev_b32_e32 v19, 16, v28
	v_and_b32_e32 v18, 0xffff0000, v28
	v_mul_f32_e32 v8, 1.0, v11
	v_mul_f32_e32 v9, 0xbfb8aa3b, v25
	v_exp_f32_e32 v9, v9
	v_lshlrev_b32_e32 v30, 16, v7
	v_and_b32_e32 v31, 0xffff0000, v7
	v_lshlrev_b32_e32 v14, 16, v29
	v_add_f32_e32 v9, 1.0, v9
	v_rcp_f32_e32 v25, v9
	v_and_b32_e32 v13, 0xffff0000, v29
	v_mul_f32_e32 v15, 0xbfb8aa3b, v15
	v_exp_f32_e32 v15, v15
	v_mul_f32_e32 v9, 1.0, v25
	v_mul_f32_e32 v11, 0xbfb8aa3b, v30
	v_exp_f32_e32 v11, v11
	v_add_f32_e32 v15, 1.0, v15
	v_mul_f32_e32 v12, 0xbfb8aa3b, v12
	v_exp_f32_e32 v12, v12
	v_add_f32_e32 v11, 1.0, v11
	v_mul_f32_e32 v20, 0xbfb8aa3b, v20
	v_exp_f32_e32 v20, v20
	v_add_f32_e32 v12, 1.0, v12
	v_mul_f32_e32 v17, 0xbfb8aa3b, v17
	v_exp_f32_e32 v17, v17
	v_add_f32_e32 v20, 1.0, v20
	v_mul_f32_e32 v24, 0xbfb8aa3b, v24
	v_exp_f32_e32 v24, v24
	v_add_f32_e32 v17, 1.0, v17
	v_mul_f32_e32 v21, 0xbfb8aa3b, v21
	v_exp_f32_e32 v21, v21
	v_add_f32_e32 v24, 1.0, v24
	v_mul_f32_e32 v23, 0xbfb8aa3b, v23
	v_exp_f32_e32 v23, v23
	v_add_f32_e32 v21, 1.0, v21
	v_mul_f32_e32 v22, 0xbfb8aa3b, v22
	v_exp_f32_e32 v22, v22
	v_add_f32_e32 v23, 1.0, v23
	v_mul_f32_e32 v19, 0xbfb8aa3b, v19
	v_exp_f32_e32 v19, v19
	v_add_f32_e32 v22, 1.0, v22
	v_mul_f32_e32 v18, 0xbfb8aa3b, v18
	v_exp_f32_e32 v18, v18
	v_add_f32_e32 v19, 1.0, v19
	v_mul_f32_e32 v14, 0xbfb8aa3b, v14
	s_waitcnt vmcnt(0) lgkmcnt(0)
	v_sub_f32_e32 v7, 1.0, v6
	v_fmac_f32_e32 v6, v7, v8
	v_cmp_gt_f32_e32 vcc, s12, v6
	v_add_f32_e32 v18, 1.0, v18
	v_exp_f32_e32 v14, v14
	v_cndmask_b32_e64 v7, 0, 32, vcc
	v_ldexp_f32 v7, v6, v7
	v_log_f32_e32 v7, v7
	v_add_f32_e32 v14, 1.0, v14
	v_mul_f32_e32 v13, 0xbfb8aa3b, v13
	v_exp_f32_e32 v13, v13
	v_mul_f32_e32 v8, 0x3f317217, v7
	v_fma_f32 v8, v7, s86, -v8
	v_fmac_f32_e32 v8, 0x3377d1cf, v7
	v_fmac_f32_e32 v8, 0x3f317217, v7
	v_cmp_lt_f32_e64 s[0:1], |v7|, s87
	v_add_f32_e32 v13, 1.0, v13
	s_nop 0
	v_cndmask_b32_e64 v7, v7, v8, s[0:1]
	v_cndmask_b32_e32 v8, 0, v231, vcc
	v_sub_f32_e32 v7, v7, v8
	ds_write_b32 v5, v7
	v_sub_f32_e32 v8, 1.0, v182
	v_fma_f32 v7, v8, v9, v182
	v_cmp_gt_f32_e32 vcc, s12, v7
	s_nop 1
	v_cndmask_b32_e64 v8, 0, 32, vcc
	v_ldexp_f32 v8, v7, v8
	v_log_f32_e32 v8, v8
	s_nop 0
	v_mul_f32_e32 v9, 0x3f317217, v8
	v_fma_f32 v9, v8, s86, -v9
	v_fmac_f32_e32 v9, 0x3377d1cf, v8
	v_fmac_f32_e32 v9, 0x3f317217, v8
	v_cmp_lt_f32_e64 s[0:1], |v8|, s87
	s_nop 1
	v_cndmask_b32_e64 v8, v8, v9, s[0:1]
	v_cndmask_b32_e32 v9, 0, v231, vcc
	v_sub_f32_e32 v8, v8, v9
	ds_write_b32 v5, v8 offset:4
	v_rcp_f32_e32 v26, v11
	v_sub_f32_e32 v9, 1.0, v183
	v_mul_f32_e32 v11, 1.0, v26
	v_mul_f32_e32 v25, 0xbfb8aa3b, v31
	v_exp_f32_e32 v25, v25
	v_fma_f32 v8, v11, v9, v183
	v_add_f32_e32 v25, 1.0, v25
	v_rcp_f32_e32 v27, v25
	s_nop 0
	v_cmp_gt_f32_e32 vcc, s12, v8
	v_mul_f32_e32 v25, 1.0, v27
	s_nop 0
	v_cndmask_b32_e64 v9, 0, 32, vcc
	v_ldexp_f32 v9, v8, v9
	v_log_f32_e32 v9, v9
	s_nop 0
	v_mul_f32_e32 v11, 0x3f317217, v9
	v_fma_f32 v11, v9, s86, -v11
	v_fmac_f32_e32 v11, 0x3377d1cf, v9
	v_fmac_f32_e32 v11, 0x3f317217, v9
	v_cmp_lt_f32_e64 s[0:1], |v9|, s87
	s_nop 1
	v_cndmask_b32_e64 v9, v9, v11, s[0:1]
	v_cndmask_b32_e32 v11, 0, v231, vcc
	v_sub_f32_e32 v9, v9, v11
	ds_write_b32 v5, v9 offset:8
	v_sub_f32_e32 v11, 1.0, v184
	v_fma_f32 v9, v25, v11, v184
	v_cmp_gt_f32_e32 vcc, s12, v9
	s_nop 1
	v_cndmask_b32_e64 v11, 0, 32, vcc
	v_ldexp_f32 v11, v9, v11
	v_log_f32_e32 v11, v11
	s_nop 0
	v_mul_f32_e32 v25, 0x3f317217, v11
	v_fma_f32 v25, v11, s86, -v25
	v_fmac_f32_e32 v25, 0x3377d1cf, v11
	v_fmac_f32_e32 v25, 0x3f317217, v11
	v_cmp_lt_f32_e64 s[0:1], |v11|, s87
	s_nop 1
	v_cndmask_b32_e64 v11, v11, v25, s[0:1]
	v_cndmask_b32_e32 v25, 0, v231, vcc
	v_sub_f32_e32 v11, v11, v25
	ds_write_b32 v5, v11 offset:12
	v_rcp_f32_e32 v27, v15
	v_sub_f32_e32 v25, 1.0, v185
	v_mul_f32_e32 v15, 1.0, v27
	v_rcp_f32_e32 v27, v12
	v_fma_f32 v11, v15, v25, v185
	v_cmp_gt_f32_e32 vcc, s12, v11
	v_mul_f32_e32 v26, 1.0, v27
	s_nop 0
	v_cndmask_b32_e64 v12, 0, 32, vcc
	v_ldexp_f32 v12, v11, v12
	v_log_f32_e32 v12, v12
	s_nop 0
	v_mul_f32_e32 v15, 0x3f317217, v12
	v_fma_f32 v15, v12, s86, -v15
	v_fmac_f32_e32 v15, 0x3377d1cf, v12
	v_fmac_f32_e32 v15, 0x3f317217, v12
	v_cmp_lt_f32_e64 s[0:1], |v12|, s87
	s_nop 1
	v_cndmask_b32_e64 v12, v12, v15, s[0:1]
	v_cndmask_b32_e32 v15, 0, v231, vcc
	v_sub_f32_e32 v12, v12, v15
	ds_write_b32 v5, v12 offset:16
	v_sub_f32_e32 v15, 1.0, v186
	v_fma_f32 v12, v26, v15, v186
	v_cmp_gt_f32_e32 vcc, s12, v12
	s_nop 1
	v_cndmask_b32_e64 v15, 0, 32, vcc
	v_ldexp_f32 v15, v12, v15
	v_log_f32_e32 v15, v15
	s_nop 0
	v_mul_f32_e32 v25, 0x3f317217, v15
	v_fma_f32 v25, v15, s86, -v25
	v_fmac_f32_e32 v25, 0x3377d1cf, v15
	v_fmac_f32_e32 v25, 0x3f317217, v15
	v_cmp_lt_f32_e64 s[0:1], |v15|, s87
	s_nop 1
	v_cndmask_b32_e64 v15, v15, v25, s[0:1]
	v_cndmask_b32_e32 v25, 0, v231, vcc
	v_sub_f32_e32 v15, v15, v25
	ds_write_b32 v5, v15 offset:20
	v_rcp_f32_e32 v27, v20
	v_sub_f32_e32 v25, 1.0, v187
	v_mul_f32_e32 v20, 1.0, v27
	v_rcp_f32_e32 v27, v17
	v_fma_f32 v15, v20, v25, v187
	v_cmp_gt_f32_e32 vcc, s12, v15
	v_mul_f32_e32 v26, 1.0, v27
	s_nop 0
	v_cndmask_b32_e64 v17, 0, 32, vcc
	v_ldexp_f32 v17, v15, v17
	v_log_f32_e32 v17, v17
	s_nop 0
	v_mul_f32_e32 v20, 0x3f317217, v17
	v_fma_f32 v20, v17, s86, -v20
	v_fmac_f32_e32 v20, 0x3377d1cf, v17
	v_fmac_f32_e32 v20, 0x3f317217, v17
	v_cmp_lt_f32_e64 s[0:1], |v17|, s87
	s_nop 1
	v_cndmask_b32_e64 v17, v17, v20, s[0:1]
	v_cndmask_b32_e32 v20, 0, v231, vcc
	v_sub_f32_e32 v17, v17, v20
	ds_write_b32 v5, v17 offset:24
	v_sub_f32_e32 v20, 1.0, v188
	v_fma_f32 v17, v26, v20, v188
	v_cmp_gt_f32_e32 vcc, s12, v17
	s_nop 1
	v_cndmask_b32_e64 v20, 0, 32, vcc
	v_ldexp_f32 v20, v17, v20
	v_log_f32_e32 v20, v20
	s_nop 0
	v_mul_f32_e32 v25, 0x3f317217, v20
	v_fma_f32 v25, v20, s86, -v25
	v_fmac_f32_e32 v25, 0x3377d1cf, v20
	v_fmac_f32_e32 v25, 0x3f317217, v20
	v_cmp_lt_f32_e64 s[0:1], |v20|, s87
	s_nop 1
	v_cndmask_b32_e64 v20, v20, v25, s[0:1]
	v_cndmask_b32_e32 v25, 0, v231, vcc
	v_sub_f32_e32 v20, v20, v25
	ds_write_b32 v5, v20 offset:28
	v_rcp_f32_e32 v27, v24
	v_sub_f32_e32 v25, 1.0, v189
	v_mul_f32_e32 v24, 1.0, v27
	v_rcp_f32_e32 v27, v21
	v_fma_f32 v20, v24, v25, v189
	v_cmp_gt_f32_e32 vcc, s12, v20
	v_mul_f32_e32 v26, 1.0, v27
	s_nop 0
	v_cndmask_b32_e64 v21, 0, 32, vcc
	v_ldexp_f32 v21, v20, v21
	v_log_f32_e32 v21, v21
	s_nop 0
	v_mul_f32_e32 v24, 0x3f317217, v21
	v_fma_f32 v24, v21, s86, -v24
	v_fmac_f32_e32 v24, 0x3377d1cf, v21
	v_fmac_f32_e32 v24, 0x3f317217, v21
	v_cmp_lt_f32_e64 s[0:1], |v21|, s87
	s_nop 1
	v_cndmask_b32_e64 v21, v21, v24, s[0:1]
	v_cndmask_b32_e32 v24, 0, v231, vcc
	v_sub_f32_e32 v21, v21, v24
	ds_write_b32 v5, v21 offset:32
	v_sub_f32_e32 v24, 1.0, v190
	v_fma_f32 v21, v26, v24, v190
	v_cmp_gt_f32_e32 vcc, s12, v21
	s_nop 1
	v_cndmask_b32_e64 v24, 0, 32, vcc
	v_ldexp_f32 v24, v21, v24
	v_log_f32_e32 v24, v24
	s_nop 0
	v_mul_f32_e32 v25, 0x3f317217, v24
	v_fma_f32 v25, v24, s86, -v25
	v_fmac_f32_e32 v25, 0x3377d1cf, v24
	v_fmac_f32_e32 v25, 0x3f317217, v24
	v_cmp_lt_f32_e64 s[0:1], |v24|, s87
	s_nop 1
	v_cndmask_b32_e64 v24, v24, v25, s[0:1]
	v_cndmask_b32_e32 v25, 0, v231, vcc
	v_sub_f32_e32 v24, v24, v25
	ds_write_b32 v5, v24 offset:36
	v_rcp_f32_e32 v27, v23
	v_sub_f32_e32 v25, 1.0, v191
	v_mul_f32_e32 v23, 1.0, v27
	v_rcp_f32_e32 v27, v22
	v_fma_f32 v24, v23, v25, v191
	v_cmp_gt_f32_e32 vcc, s12, v24
	v_mul_f32_e32 v26, 1.0, v27
	s_nop 0
	v_cndmask_b32_e64 v22, 0, 32, vcc
	v_ldexp_f32 v22, v24, v22
	v_log_f32_e32 v22, v22
	s_nop 0
	v_mul_f32_e32 v23, 0x3f317217, v22
	v_fma_f32 v23, v22, s86, -v23
	v_fmac_f32_e32 v23, 0x3377d1cf, v22
	v_fmac_f32_e32 v23, 0x3f317217, v22
	v_cmp_lt_f32_e64 s[0:1], |v22|, s87
	s_nop 1
	v_cndmask_b32_e64 v22, v22, v23, s[0:1]
	v_cndmask_b32_e32 v23, 0, v231, vcc
	v_sub_f32_e32 v22, v22, v23
	ds_write_b32 v5, v22 offset:40
	v_sub_f32_e32 v23, 1.0, v238
	v_fma_f32 v22, v26, v23, v238
	v_cmp_gt_f32_e32 vcc, s12, v22
	s_nop 1
	v_cndmask_b32_e64 v23, 0, 32, vcc
	v_ldexp_f32 v23, v22, v23
	v_log_f32_e32 v23, v23
	s_nop 0
	v_mul_f32_e32 v25, 0x3f317217, v23
	v_fma_f32 v25, v23, s86, -v25
	v_fmac_f32_e32 v25, 0x3377d1cf, v23
	v_fmac_f32_e32 v25, 0x3f317217, v23
	v_cmp_lt_f32_e64 s[0:1], |v23|, s87
	s_nop 1
	v_cndmask_b32_e64 v23, v23, v25, s[0:1]
	v_cndmask_b32_e32 v25, 0, v231, vcc
	v_sub_f32_e32 v23, v23, v25
	ds_write_b32 v5, v23 offset:44
	v_rcp_f32_e32 v27, v19
	v_sub_f32_e32 v25, 1.0, v239
	v_mul_f32_e32 v19, 1.0, v27
	v_rcp_f32_e32 v27, v18
	v_fma_f32 v23, v19, v25, v239
	v_cmp_gt_f32_e32 vcc, s12, v23
	v_mul_f32_e32 v26, 1.0, v27
	s_nop 0
	v_cndmask_b32_e64 v18, 0, 32, vcc
	v_ldexp_f32 v18, v23, v18
	v_log_f32_e32 v18, v18
	s_nop 0
	v_mul_f32_e32 v19, 0x3f317217, v18
	v_fma_f32 v19, v18, s86, -v19
	v_fmac_f32_e32 v19, 0x3377d1cf, v18
	v_fmac_f32_e32 v19, 0x3f317217, v18
	v_cmp_lt_f32_e64 s[0:1], |v18|, s87
	s_nop 1
	v_cndmask_b32_e64 v18, v18, v19, s[0:1]
	v_cndmask_b32_e32 v19, 0, v231, vcc
	v_sub_f32_e32 v18, v18, v19
	ds_write_b32 v5, v18 offset:48
	v_sub_f32_e32 v19, 1.0, v240
	v_fma_f32 v18, v26, v19, v240
	v_cmp_gt_f32_e32 vcc, s12, v18
	s_nop 1
	v_cndmask_b32_e64 v19, 0, 32, vcc
	v_ldexp_f32 v19, v18, v19
	v_log_f32_e32 v19, v19
	s_nop 0
	v_mul_f32_e32 v25, 0x3f317217, v19
	v_fma_f32 v25, v19, s86, -v25
	v_fmac_f32_e32 v25, 0x3377d1cf, v19
	v_fmac_f32_e32 v25, 0x3f317217, v19
	v_cmp_lt_f32_e64 s[0:1], |v19|, s87
	s_nop 1
	v_cndmask_b32_e64 v19, v19, v25, s[0:1]
	v_cndmask_b32_e32 v25, 0, v231, vcc
	v_sub_f32_e32 v19, v19, v25
	ds_write_b32 v5, v19 offset:52
	v_rcp_f32_e32 v27, v14
	v_sub_f32_e32 v19, 1.0, v241
	v_mul_f32_e32 v14, 1.0, v27
	v_rcp_f32_e32 v27, v13
	v_fma_f32 v25, v14, v19, v241
	v_cmp_gt_f32_e32 vcc, s12, v25
	v_mul_f32_e32 v13, 1.0, v27
	s_nop 0
	v_cndmask_b32_e64 v14, 0, 32, vcc
	v_ldexp_f32 v14, v25, v14
	v_log_f32_e32 v14, v14
	s_nop 0
	v_mul_f32_e32 v19, 0x3f317217, v14
	v_fma_f32 v19, v14, s86, -v19
	v_fmac_f32_e32 v19, 0x3377d1cf, v14
	v_fmac_f32_e32 v19, 0x3f317217, v14
	v_cmp_lt_f32_e64 s[0:1], |v14|, s87
	s_nop 1
	v_cndmask_b32_e64 v14, v14, v19, s[0:1]
	v_cndmask_b32_e32 v19, 0, v231, vcc
	v_sub_f32_e32 v14, v14, v19
	ds_write_b32 v5, v14 offset:56
	v_sub_f32_e32 v2, 1.0, v242
	v_fma_f32 v3, v13, v2, v242
	v_cmp_gt_f32_e32 vcc, s12, v3
	s_nop 1
	v_cndmask_b32_e64 v2, 0, 32, vcc
	v_ldexp_f32 v2, v3, v2
	v_log_f32_e32 v2, v2
	s_nop 0
	v_mul_f32_e32 v13, 0x3f317217, v2
	v_fma_f32 v13, v2, s86, -v13
	v_fmac_f32_e32 v13, 0x3377d1cf, v2
	v_fmac_f32_e32 v13, 0x3f317217, v2
	v_cmp_lt_f32_e64 s[0:1], |v2|, s87
	s_nop 1
	v_cndmask_b32_e64 v2, v2, v13, s[0:1]
	v_cndmask_b32_e32 v13, 0, v231, vcc
	v_sub_f32_e32 v2, v2, v13
	v_ashrrev_i32_e32 v13, 7, v10
	v_and_b32_e32 v10, 0x7f, v10
	v_lshlrev_b32_e32 v14, 13, v13
	v_lshlrev_b32_e32 v19, 2, v10
	ds_write_b32 v5, v2 offset:60
	v_add3_u32 v2, 0, v19, v14
	s_mov_b64 s[0:1], -1
	s_and_b64 vcc, exec, s[2:3]
	s_waitcnt lgkmcnt(0)
	s_barrier
	s_cbranch_vccz .LBB0_598
	ds_read2st64_b32 v[166:167], v2 offset0:28 offset1:30
	ds_read2st64_b32 v[168:169], v2 offset0:24 offset1:26
	ds_read2st64_b32 v[170:171], v2 offset0:20 offset1:22
	ds_read2st64_b32 v[172:173], v2 offset0:16 offset1:18
	ds_read2st64_b32 v[174:175], v2 offset0:12 offset1:14
	ds_read2st64_b32 v[176:177], v2 offset0:8 offset1:10
	ds_read2st64_b32 v[178:179], v2 offset0:4 offset1:6
	ds_read2st64_b32 v[180:181], v2 offset1:2
	s_mov_b64 s[0:1], 0
	s_waitcnt lgkmcnt(0)
	v_add_f32_e32 v27, 0, v167
	v_add_f32_e32 v28, v27, v166
	ds_write2st64_b32 v2, v28, v27 offset0:28 offset1:30
	v_add_f32_e32 v27, v28, v169
	v_add_f32_e32 v28, v27, v168
	ds_write2st64_b32 v2, v28, v27 offset0:24 offset1:26
	v_add_f32_e32 v27, v28, v171
	v_add_f32_e32 v28, v27, v170
	ds_write2st64_b32 v2, v28, v27 offset0:20 offset1:22
	v_add_f32_e32 v27, v28, v173
	v_add_f32_e32 v28, v27, v172
	ds_write2st64_b32 v2, v28, v27 offset0:16 offset1:18
	v_add_f32_e32 v27, v28, v175
	v_add_f32_e32 v28, v27, v174
	ds_write2st64_b32 v2, v28, v27 offset0:12 offset1:14
	v_add_f32_e32 v27, v28, v177
	v_add_f32_e32 v28, v27, v176
	ds_write2st64_b32 v2, v28, v27 offset0:8 offset1:10
	v_add_f32_e32 v27, v28, v179
	v_add_f32_e32 v28, v27, v178
	ds_write2st64_b32 v2, v28, v27 offset0:4 offset1:6
	v_add_f32_e32 v27, v28, v181
	v_add_f32_e32 v26, v27, v180
	ds_write2st64_b32 v2, v26, v27 offset1:2

.LBB0_736:
	s_xor_b64 s[18:19], s[92:93], -1
	s_or_b32 s0, s95, s23
	s_mul_hi_i32 s8, s0, 0x84
	s_mul_i32 s9, s0, 0x84
	s_and_b64 s[0:1], s[92:93], exec
	s_cselect_b32 s0, s21, s94
	s_ashr_i32 s1, s0, 31
	s_add_u32 s0, s9, s0
	s_addc_u32 s1, s8, s1
	s_lshl_b64 s[0:1], s[0:1], 15
	v_lshl_add_u64 v[16:17], v[86:87], 0, s[0:1]
	global_load_dwordx4 v[60:63], v[16:17], off
	global_load_dwordx4 v[56:59], v[16:17], off offset:32
	global_load_dwordx4 v[52:55], v[16:17], off offset:64
	global_load_dwordx4 v[48:51], v[16:17], off offset:96
	global_load_dwordx4 v[44:47], v[16:17], off offset:128
	global_load_dwordx4 v[40:43], v[16:17], off offset:160
	global_load_dwordx4 v[36:39], v[16:17], off offset:192
	global_load_dwordx4 v[32:35], v[16:17], off offset:224
	v_mov_b32_e32 v113, v207
	s_and_b64 vcc, exec, s[96:97]
	v_ashrrev_i32_e32 v110, 3, v113
	v_lshlrev_b32_e32 v16, 4, v113
	v_and_b32_e32 v111, 0x70, v16
	v_add_u32_e32 v18, s22, v110
	v_mov_b64_e32 v[16:17], s[2:3]
	v_mad_i64_i32 v[16:17], s[0:1], v18, s14, v[16:17]
	v_lshlrev_b32_e32 v128, 1, v111
	v_lshl_add_u64 v[90:91], v[16:17], 0, v[128:129]
	v_lshlrev_b32_e32 v16, 9, v110
	v_lshlrev_b32_e32 v17, 2, v111
	v_add3_u32 v109, 0, v16, v17
	s_mov_b64 s[0:1], -1
	s_cbranch_vccz .LBB0_754
	s_and_b64 s[0:1], s[92:93], exec
	s_cselect_b32 s26, s15, 0x1800
	v_lshl_add_u64 v[20:21], v[90:91], 0, s[26:27]
	global_load_dwordx4 v[16:19], v[20:21], off
	global_load_dwordx4 v[116:119], v[20:21], off offset:16
	s_waitcnt vmcnt(0) lgkmcnt(0)
	v_lshlrev_b32_e32 v20, 16, v16
	v_and_b32_e32 v112, 0xffff0000, v16
	v_or_b32_e32 v16, s20, v111
	v_lshlrev_b32_e32 v128, 2, v16
	v_lshlrev_b32_e32 v115, 16, v17
	v_and_b32_e32 v120, 0xffff0000, v17
	v_lshl_add_u64 v[16:17], s[78:79], 0, v[128:129]
	global_load_dword v111, v[16:17], off
	global_load_dword v182, v[16:17], off offset:4
	global_load_dword v183, v[16:17], off offset:8
	global_load_dword v184, v[16:17], off offset:12
	global_load_dword v185, v[16:17], off offset:16
	global_load_dword v186, v[16:17], off offset:20
	global_load_dword v187, v[16:17], off offset:24
	global_load_dword v188, v[16:17], off offset:28
	global_load_dword v189, v[16:17], off offset:32
	global_load_dword v190, v[16:17], off offset:36
	global_load_dword v191, v[16:17], off offset:40
	global_load_dword v238, v[16:17], off offset:44
	global_load_dword v239, v[16:17], off offset:48
	global_load_dword v240, v[16:17], off offset:52
	global_load_dword v241, v[16:17], off offset:56
	global_load_dword v242, v[16:17], off offset:60
	v_lshlrev_b32_e32 v31, 16, v19
	v_and_b32_e32 v30, 0xffff0000, v19
	v_mul_f32_e32 v19, 0xbfb8aa3b, v20
	v_exp_f32_e32 v19, v19
	v_lshlrev_b32_e32 v29, 16, v116
	v_and_b32_e32 v28, 0xffff0000, v116
	v_lshlrev_b32_e32 v27, 16, v117
	v_add_f32_e32 v19, 1.0, v19
	v_rcp_f32_e32 v116, v19
	v_and_b32_e32 v26, 0xffff0000, v117
	v_lshlrev_b32_e32 v25, 16, v118
	v_and_b32_e32 v24, 0xffff0000, v118
	v_lshlrev_b32_e32 v23, 16, v119
	v_and_b32_e32 v22, 0xffff0000, v119
	v_mul_f32_e32 v19, 1.0, v116
	v_mul_f32_e32 v20, 0xbfb8aa3b, v112
	v_exp_f32_e32 v20, v20
	v_lshlrev_b32_e32 v114, 16, v18
	v_and_b32_e32 v21, 0xffff0000, v18
	v_mul_f32_e32 v114, 0xbfb8aa3b, v114
	v_add_f32_e32 v20, 1.0, v20
	v_rcp_f32_e32 v116, v20
	v_exp_f32_e32 v114, v114
	v_mul_f32_e32 v21, 0xbfb8aa3b, v21
	v_exp_f32_e32 v21, v21
	v_mul_f32_e32 v20, 1.0, v116
	v_add_f32_e32 v114, 1.0, v114
	v_add_f32_e32 v21, 1.0, v21
	v_mul_f32_e32 v31, 0xbfb8aa3b, v31
	v_exp_f32_e32 v31, v31
	v_mul_f32_e32 v30, 0xbfb8aa3b, v30
	v_exp_f32_e32 v30, v30
	v_mul_f32_e32 v29, 0xbfb8aa3b, v29
	v_add_f32_e32 v31, 1.0, v31
	v_exp_f32_e32 v29, v29
	v_add_f32_e32 v30, 1.0, v30
	v_mul_f32_e32 v28, 0xbfb8aa3b, v28
	v_exp_f32_e32 v28, v28
	v_add_f32_e32 v29, 1.0, v29
	v_mul_f32_e32 v27, 0xbfb8aa3b, v27
	v_exp_f32_e32 v27, v27
	v_add_f32_e32 v28, 1.0, v28
	v_mul_f32_e32 v26, 0xbfb8aa3b, v26
	v_exp_f32_e32 v26, v26
	v_add_f32_e32 v27, 1.0, v27
	v_mul_f32_e32 v25, 0xbfb8aa3b, v25
	v_exp_f32_e32 v25, v25
	v_add_f32_e32 v26, 1.0, v26
	v_mul_f32_e32 v24, 0xbfb8aa3b, v24
	v_exp_f32_e32 v24, v24
	v_add_f32_e32 v25, 1.0, v25
	v_mul_f32_e32 v23, 0xbfb8aa3b, v23
	v_exp_f32_e32 v23, v23
	v_add_f32_e32 v24, 1.0, v24
	v_mul_f32_e32 v22, 0xbfb8aa3b, v22
	v_exp_f32_e32 v22, v22
	v_add_f32_e32 v23, 1.0, v23
	s_waitcnt vmcnt(0) lgkmcnt(0)
	v_sub_f32_e32 v18, 1.0, v111
	v_fmac_f32_e32 v111, v18, v19
	v_cmp_gt_f32_e32 vcc, s12, v111
	v_add_f32_e32 v22, 1.0, v22
	s_nop 0
	v_cndmask_b32_e64 v18, 0, 32, vcc
	v_ldexp_f32 v18, v111, v18
	v_log_f32_e32 v18, v18
	s_nop 0
	v_mul_f32_e32 v19, 0x3f317217, v18
	v_fma_f32 v19, v18, s86, -v19
	v_fmac_f32_e32 v19, 0x3377d1cf, v18
	v_fmac_f32_e32 v19, 0x3f317217, v18
	v_cmp_lt_f32_e64 s[0:1], |v18|, s87
	s_nop 1
	v_cndmask_b32_e64 v18, v18, v19, s[0:1]
	v_cndmask_b32_e32 v19, 0, v231, vcc
	v_sub_f32_e32 v18, v18, v19
	ds_write_b32 v109, v18
	v_sub_f32_e32 v18, 1.0, v182
	v_fma_f32 v112, v18, v20, v182
	v_cmp_gt_f32_e32 vcc, s12, v112
	v_mul_f32_e32 v20, 0xbfb8aa3b, v115
	v_exp_f32_e32 v20, v20
	v_cndmask_b32_e64 v18, 0, 32, vcc
	v_ldexp_f32 v18, v112, v18
	v_log_f32_e32 v18, v18
	v_add_f32_e32 v20, 1.0, v20
	v_mul_f32_e32 v19, 0x3f317217, v18
	v_fma_f32 v19, v18, s86, -v19
	v_fmac_f32_e32 v19, 0x3377d1cf, v18
	v_fmac_f32_e32 v19, 0x3f317217, v18
	v_cmp_lt_f32_e64 s[0:1], |v18|, s87
	s_nop 1
	v_cndmask_b32_e64 v18, v18, v19, s[0:1]
	v_cndmask_b32_e32 v19, 0, v231, vcc
	v_sub_f32_e32 v18, v18, v19
	ds_write_b32 v109, v18 offset:4
	v_rcp_f32_e32 v116, v20
	v_sub_f32_e32 v19, 1.0, v183
	v_mul_f32_e32 v20, 1.0, v116
	v_mul_f32_e32 v115, 0xbfb8aa3b, v120
	v_exp_f32_e32 v115, v115
	v_fma_f32 v18, v20, v19, v183
	v_add_f32_e32 v115, 1.0, v115
	v_rcp_f32_e32 v117, v115
	s_nop 0
	v_cmp_gt_f32_e32 vcc, s12, v18
	v_mul_f32_e32 v115, 1.0, v117
	s_nop 0
	v_cndmask_b32_e64 v19, 0, 32, vcc
	v_ldexp_f32 v19, v18, v19
	v_log_f32_e32 v19, v19
	s_nop 0
	v_mul_f32_e32 v20, 0x3f317217, v19
	v_fma_f32 v20, v19, s86, -v20
	v_fmac_f32_e32 v20, 0x3377d1cf, v19
	v_fmac_f32_e32 v20, 0x3f317217, v19
	v_cmp_lt_f32_e64 s[0:1], |v19|, s87
	s_nop 1
	v_cndmask_b32_e64 v19, v19, v20, s[0:1]
	v_cndmask_b32_e32 v20, 0, v231, vcc
	v_sub_f32_e32 v19, v19, v20
	ds_write_b32 v109, v19 offset:8
	v_sub_f32_e32 v20, 1.0, v184
	v_fma_f32 v19, v115, v20, v184
	v_cmp_gt_f32_e32 vcc, s12, v19
	s_nop 1
	v_cndmask_b32_e64 v20, 0, 32, vcc
	v_ldexp_f32 v20, v19, v20
	v_log_f32_e32 v20, v20
	s_nop 0
	v_mul_f32_e32 v115, 0x3f317217, v20
	v_fma_f32 v115, v20, s86, -v115
	v_fmac_f32_e32 v115, 0x3377d1cf, v20
	v_fmac_f32_e32 v115, 0x3f317217, v20
	v_cmp_lt_f32_e64 s[0:1], |v20|, s87
	s_nop 1
	v_cndmask_b32_e64 v20, v20, v115, s[0:1]
	v_cndmask_b32_e32 v115, 0, v231, vcc
	v_sub_f32_e32 v20, v20, v115
	ds_write_b32 v109, v20 offset:12
	v_rcp_f32_e32 v117, v114
	v_sub_f32_e32 v115, 1.0, v185
	v_mul_f32_e32 v114, 1.0, v117
	v_rcp_f32_e32 v117, v21
	v_fma_f32 v20, v114, v115, v185
	v_cmp_gt_f32_e32 vcc, s12, v20
	v_mul_f32_e32 v116, 1.0, v117
	s_nop 0
	v_cndmask_b32_e64 v21, 0, 32, vcc
	v_ldexp_f32 v21, v20, v21
	v_log_f32_e32 v21, v21
	s_nop 0
	v_mul_f32_e32 v114, 0x3f317217, v21
	v_fma_f32 v114, v21, s86, -v114
	v_fmac_f32_e32 v114, 0x3377d1cf, v21
	v_fmac_f32_e32 v114, 0x3f317217, v21
	v_cmp_lt_f32_e64 s[0:1], |v21|, s87
	s_nop 1
	v_cndmask_b32_e64 v21, v21, v114, s[0:1]
	v_cndmask_b32_e32 v114, 0, v231, vcc
	v_sub_f32_e32 v21, v21, v114
	ds_write_b32 v109, v21 offset:16
	v_sub_f32_e32 v114, 1.0, v186
	v_fma_f32 v21, v116, v114, v186
	v_cmp_gt_f32_e32 vcc, s12, v21
	s_nop 1
	v_cndmask_b32_e64 v114, 0, 32, vcc
	v_ldexp_f32 v114, v21, v114
	v_log_f32_e32 v114, v114
	s_nop 0
	v_mul_f32_e32 v115, 0x3f317217, v114
	v_fma_f32 v115, v114, s86, -v115
	v_fmac_f32_e32 v115, 0x3377d1cf, v114
	v_fmac_f32_e32 v115, 0x3f317217, v114
	v_cmp_lt_f32_e64 s[0:1], |v114|, s87
	s_nop 1
	v_cndmask_b32_e64 v114, v114, v115, s[0:1]
	v_cndmask_b32_e32 v115, 0, v231, vcc
	v_sub_f32_e32 v114, v114, v115
	ds_write_b32 v109, v114 offset:20
	v_rcp_f32_e32 v117, v31
	v_sub_f32_e32 v115, 1.0, v187
	v_mul_f32_e32 v31, 1.0, v117
	v_rcp_f32_e32 v117, v30
	v_fma_f32 v114, v31, v115, v187
	v_cmp_gt_f32_e32 vcc, s12, v114
	v_mul_f32_e32 v30, 1.0, v117
	s_nop 0
	v_cndmask_b32_e64 v31, 0, 32, vcc
	v_ldexp_f32 v31, v114, v31
	v_log_f32_e32 v31, v31
	s_nop 0
	v_mul_f32_e32 v115, 0x3f317217, v31
	v_fma_f32 v115, v31, s86, -v115
	v_fmac_f32_e32 v115, 0x3377d1cf, v31
	v_fmac_f32_e32 v115, 0x3f317217, v31
	v_cmp_lt_f32_e64 s[0:1], |v31|, s87
	s_nop 1
	v_cndmask_b32_e64 v31, v31, v115, s[0:1]
	v_cndmask_b32_e32 v115, 0, v231, vcc
	v_sub_f32_e32 v31, v31, v115
	ds_write_b32 v109, v31 offset:24
	v_sub_f32_e32 v31, 1.0, v188
	v_fma_f32 v115, v30, v31, v188
	v_cmp_gt_f32_e32 vcc, s12, v115
	s_nop 1
	v_cndmask_b32_e64 v30, 0, 32, vcc
	v_ldexp_f32 v30, v115, v30
	v_log_f32_e32 v30, v30
	s_nop 0
	v_mul_f32_e32 v31, 0x3f317217, v30
	v_fma_f32 v31, v30, s86, -v31
	v_fmac_f32_e32 v31, 0x3377d1cf, v30
	v_fmac_f32_e32 v31, 0x3f317217, v30
	v_cmp_lt_f32_e64 s[0:1], |v30|, s87
	s_nop 1
	v_cndmask_b32_e64 v30, v30, v31, s[0:1]
	v_cndmask_b32_e32 v31, 0, v231, vcc
	v_sub_f32_e32 v30, v30, v31
	ds_write_b32 v109, v30 offset:28
	v_rcp_f32_e32 v117, v29
	v_sub_f32_e32 v30, 1.0, v189
	v_mul_f32_e32 v29, 1.0, v117
	v_rcp_f32_e32 v117, v28
	v_fma_f32 v116, v29, v30, v189
	v_cmp_gt_f32_e32 vcc, s12, v116
	v_mul_f32_e32 v28, 1.0, v117
	s_nop 0
	v_cndmask_b32_e64 v29, 0, 32, vcc
	v_ldexp_f32 v29, v116, v29
	v_log_f32_e32 v29, v29
	s_nop 0
	v_mul_f32_e32 v30, 0x3f317217, v29
	v_fma_f32 v30, v29, s86, -v30
	v_fmac_f32_e32 v30, 0x3377d1cf, v29
	v_fmac_f32_e32 v30, 0x3f317217, v29
	v_cmp_lt_f32_e64 s[0:1], |v29|, s87
	s_nop 1
	v_cndmask_b32_e64 v29, v29, v30, s[0:1]
	v_cndmask_b32_e32 v30, 0, v231, vcc
	v_sub_f32_e32 v29, v29, v30
	ds_write_b32 v109, v29 offset:32
	v_sub_f32_e32 v29, 1.0, v190
	v_fma_f32 v117, v28, v29, v190
	v_cmp_gt_f32_e32 vcc, s12, v117
	s_nop 1
	v_cndmask_b32_e64 v28, 0, 32, vcc
	v_ldexp_f32 v28, v117, v28
	v_log_f32_e32 v28, v28
	s_nop 0
	v_mul_f32_e32 v29, 0x3f317217, v28
	v_fma_f32 v29, v28, s86, -v29
	v_fmac_f32_e32 v29, 0x3377d1cf, v28
	v_fmac_f32_e32 v29, 0x3f317217, v28
	v_cmp_lt_f32_e64 s[0:1], |v28|, s87
	s_nop 1
	v_cndmask_b32_e64 v28, v28, v29, s[0:1]
	v_cndmask_b32_e32 v29, 0, v231, vcc
	v_sub_f32_e32 v28, v28, v29
	ds_write_b32 v109, v28 offset:36
	v_rcp_f32_e32 v30, v27
	v_sub_f32_e32 v28, 1.0, v191
	v_mul_f32_e32 v27, 1.0, v30
	v_rcp_f32_e32 v30, v26
	v_fma_f32 v118, v27, v28, v191
	v_cmp_gt_f32_e32 vcc, s12, v118
	v_mul_f32_e32 v29, 1.0, v30
	s_nop 0
	v_cndmask_b32_e64 v26, 0, 32, vcc
	v_ldexp_f32 v26, v118, v26
	v_log_f32_e32 v26, v26
	s_nop 0
	v_mul_f32_e32 v27, 0x3f317217, v26
	v_fma_f32 v27, v26, s86, -v27
	v_fmac_f32_e32 v27, 0x3377d1cf, v26
	v_fmac_f32_e32 v27, 0x3f317217, v26
	v_cmp_lt_f32_e64 s[0:1], |v26|, s87
	s_nop 1
	v_cndmask_b32_e64 v26, v26, v27, s[0:1]
	v_cndmask_b32_e32 v27, 0, v231, vcc
	v_sub_f32_e32 v26, v26, v27
	ds_write_b32 v109, v26 offset:40
	v_sub_f32_e32 v27, 1.0, v238
	v_fma_f32 v26, v29, v27, v238
	v_cmp_gt_f32_e32 vcc, s12, v26
	s_nop 1
	v_cndmask_b32_e64 v27, 0, 32, vcc
	v_ldexp_f32 v27, v26, v27
	v_log_f32_e32 v27, v27
	s_nop 0
	v_mul_f32_e32 v28, 0x3f317217, v27
	v_fma_f32 v28, v27, s86, -v28
	v_fmac_f32_e32 v28, 0x3377d1cf, v27
	v_fmac_f32_e32 v28, 0x3f317217, v27
	v_cmp_lt_f32_e64 s[0:1], |v27|, s87
	s_nop 1
	v_cndmask_b32_e64 v27, v27, v28, s[0:1]
	v_cndmask_b32_e32 v28, 0, v231, vcc
	v_sub_f32_e32 v27, v27, v28
	ds_write_b32 v109, v27 offset:44
	v_rcp_f32_e32 v30, v25
	v_sub_f32_e32 v28, 1.0, v239
	v_mul_f32_e32 v25, 1.0, v30
	v_rcp_f32_e32 v30, v24
	v_fma_f32 v27, v25, v28, v239
	v_cmp_gt_f32_e32 vcc, s12, v27
	v_mul_f32_e32 v29, 1.0, v30
	s_nop 0
	v_cndmask_b32_e64 v24, 0, 32, vcc
	v_ldexp_f32 v24, v27, v24
	v_log_f32_e32 v24, v24
	s_nop 0
	v_mul_f32_e32 v25, 0x3f317217, v24
	v_fma_f32 v25, v24, s86, -v25
	v_fmac_f32_e32 v25, 0x3377d1cf, v24
	v_fmac_f32_e32 v25, 0x3f317217, v24
	v_cmp_lt_f32_e64 s[0:1], |v24|, s87
	s_nop 1
	v_cndmask_b32_e64 v24, v24, v25, s[0:1]
	v_cndmask_b32_e32 v25, 0, v231, vcc
	v_sub_f32_e32 v24, v24, v25
	ds_write_b32 v109, v24 offset:48
	v_sub_f32_e32 v25, 1.0, v240
	v_fma_f32 v24, v29, v25, v240
	v_cmp_gt_f32_e32 vcc, s12, v24
	s_nop 1
	v_cndmask_b32_e64 v25, 0, 32, vcc
	v_ldexp_f32 v25, v24, v25
	v_log_f32_e32 v25, v25
	s_nop 0
	v_mul_f32_e32 v28, 0x3f317217, v25
	v_fma_f32 v28, v25, s86, -v28
	v_fmac_f32_e32 v28, 0x3377d1cf, v25
	v_fmac_f32_e32 v28, 0x3f317217, v25
	v_cmp_lt_f32_e64 s[0:1], |v25|, s87
	s_nop 1
	v_cndmask_b32_e64 v25, v25, v28, s[0:1]
	v_cndmask_b32_e32 v28, 0, v231, vcc
	v_sub_f32_e32 v25, v25, v28
	ds_write_b32 v109, v25 offset:52
	v_rcp_f32_e32 v30, v23
	v_sub_f32_e32 v28, 1.0, v241
	v_mul_f32_e32 v23, 1.0, v30
	v_rcp_f32_e32 v30, v22
	v_fma_f32 v25, v23, v28, v241
	v_cmp_gt_f32_e32 vcc, s12, v25
	v_mul_f32_e32 v22, 1.0, v30
	s_nop 0
	v_cndmask_b32_e64 v23, 0, 32, vcc
	v_ldexp_f32 v23, v25, v23
	v_log_f32_e32 v23, v23
	s_nop 0
	v_mul_f32_e32 v28, 0x3f317217, v23
	v_fma_f32 v28, v23, s86, -v28
	v_fmac_f32_e32 v28, 0x3377d1cf, v23
	v_fmac_f32_e32 v28, 0x3f317217, v23
	v_cmp_lt_f32_e64 s[0:1], |v23|, s87
	s_nop 1
	v_cndmask_b32_e64 v23, v23, v28, s[0:1]
	v_cndmask_b32_e32 v28, 0, v231, vcc
	v_sub_f32_e32 v23, v23, v28
	ds_write_b32 v109, v23 offset:56
	v_sub_f32_e32 v17, 1.0, v242
	v_fma_f32 v16, v22, v17, v242
	v_cmp_gt_f32_e32 vcc, s12, v16
	s_nop 1
	v_cndmask_b32_e64 v17, 0, 32, vcc
	v_ldexp_f32 v17, v16, v17
	v_log_f32_e32 v17, v17
	s_nop 0
	v_mul_f32_e32 v22, 0x3f317217, v17
	v_fma_f32 v22, v17, s86, -v22
	v_fmac_f32_e32 v22, 0x3377d1cf, v17
	v_fmac_f32_e32 v22, 0x3f317217, v17
	v_cmp_lt_f32_e64 s[0:1], |v17|, s87
	s_nop 1
	v_cndmask_b32_e64 v17, v17, v22, s[0:1]
	v_cndmask_b32_e32 v22, 0, v231, vcc
	v_sub_f32_e32 v17, v17, v22
	ds_write_b32 v109, v17 offset:60
	v_ashrrev_i32_e32 v17, 7, v113
	v_and_b32_e32 v22, 0x7f, v113
	v_lshlrev_b32_e32 v23, 13, v17
	v_lshlrev_b32_e32 v28, 2, v22
	v_add3_u32 v113, 0, v28, v23
	s_mov_b64 s[0:1], -1
	s_and_b64 vcc, exec, s[18:19]
	s_waitcnt lgkmcnt(0)
	s_barrier
	s_cbranch_vccz .LBB0_739
	ds_read2st64_b32 v[166:167], v113 offset0:28 offset1:30
	ds_read2st64_b32 v[168:169], v113 offset0:24 offset1:26
	ds_read2st64_b32 v[170:171], v113 offset0:20 offset1:22
	ds_read2st64_b32 v[172:173], v113 offset0:16 offset1:18
	ds_read2st64_b32 v[174:175], v113 offset0:12 offset1:14
	ds_read2st64_b32 v[176:177], v113 offset0:8 offset1:10
	ds_read2st64_b32 v[178:179], v113 offset0:4 offset1:6
	ds_read2st64_b32 v[180:181], v113 offset1:2
	s_mov_b64 s[0:1], 0
	s_waitcnt lgkmcnt(0)
	v_add_f32_e32 v29, 0, v167
	v_add_f32_e32 v119, v29, v166
	ds_write2st64_b32 v113, v119, v29 offset0:28 offset1:30
	v_add_f32_e32 v29, v119, v169
	v_add_f32_e32 v119, v29, v168
	ds_write2st64_b32 v113, v119, v29 offset0:24 offset1:26
	v_add_f32_e32 v29, v119, v171
	v_add_f32_e32 v119, v29, v170
	ds_write2st64_b32 v113, v119, v29 offset0:20 offset1:22
	v_add_f32_e32 v29, v119, v173
	v_add_f32_e32 v119, v29, v172
	ds_write2st64_b32 v113, v119, v29 offset0:16 offset1:18
	v_add_f32_e32 v29, v119, v175
	v_add_f32_e32 v119, v29, v174
	ds_write2st64_b32 v113, v119, v29 offset0:12 offset1:14
	v_add_f32_e32 v29, v119, v177
	v_add_f32_e32 v119, v29, v176
	ds_write2st64_b32 v113, v119, v29 offset0:8 offset1:10
	v_add_f32_e32 v29, v119, v179
	v_add_f32_e32 v119, v29, v178
	ds_write2st64_b32 v113, v119, v29 offset0:4 offset1:6
	v_add_f32_e32 v29, v119, v181
	v_add_f32_e32 v30, v29, v180
	ds_write2st64_b32 v113, v30, v29 offset1:2
